# GEMM K-loops: next-tile global loads issued in G2 right behind the LDS writes that free their staging registers (quarter iteration more prefetch lead), G3 is a pure MFMA burst
# baseline (speedup 1.0000x reference)
.Lg2_p4_loop:
	ds_read_b128 v[196:199], v223 offset:8192
	ds_read_b128 v[200:203], v223 offset:10240
	ds_read_b128 v[204:207], v223 offset:12288
	ds_read_b128 v[208:211], v223 offset:14336
	s_waitcnt lgkmcnt(4)
	v_mfma_f32_16x16x32_bf16 v[126:129], v[212:215], v[180:183], v[126:129]
	v_mfma_f32_16x16x32_bf16 v[122:125], v[218:221], v[180:183], v[122:125]
	v_mfma_f32_16x16x32_bf16 v[118:121], v[224:227], v[180:183], v[118:121]
	v_mfma_f32_16x16x32_bf16 v[114:117], v[228:231], v[180:183], v[114:117]
	v_mfma_f32_16x16x32_bf16 v[110:113], v[212:215], v[184:187], v[110:113]
	v_mfma_f32_16x16x32_bf16 v[106:109], v[218:221], v[184:187], v[106:109]
	v_mfma_f32_16x16x32_bf16 v[102:105], v[224:227], v[184:187], v[102:105]
	v_mfma_f32_16x16x32_bf16 v[98:101], v[228:231], v[184:187], v[98:101]
	v_mfma_f32_16x16x32_bf16 v[94:97], v[212:215], v[188:191], v[94:97]
	v_mfma_f32_16x16x32_bf16 v[90:93], v[218:221], v[188:191], v[90:93]
	v_mfma_f32_16x16x32_bf16 v[86:89], v[224:227], v[188:191], v[86:89]
	v_mfma_f32_16x16x32_bf16 v[82:85], v[228:231], v[188:191], v[82:85]
	v_mfma_f32_16x16x32_bf16 v[78:81], v[212:215], v[192:195], v[78:81]
	v_mfma_f32_16x16x32_bf16 v[74:77], v[218:221], v[192:195], v[74:77]
	v_mfma_f32_16x16x32_bf16 v[70:73], v[224:227], v[192:195], v[70:73]
	v_mfma_f32_16x16x32_bf16 v[66:69], v[228:231], v[192:195], v[66:69]
	ds_read_b128 v[180:183], v216
	ds_read_b128 v[184:187], v216 offset:2048
	ds_read_b128 v[188:191], v216 offset:4096
	ds_read_b128 v[192:195], v216 offset:6144
	ds_read_b128 v[232:235], v217
	ds_read_b128 v[236:239], v217 offset:2048
	ds_read_b128 v[240:243], v217 offset:4096
	ds_read_b128 v[244:247], v217 offset:6144
	s_waitcnt lgkmcnt(8)
	v_mfma_f32_16x16x32_bf16 v[62:65], v[212:215], v[196:199], v[62:65]
	v_mfma_f32_16x16x32_bf16 v[58:61], v[218:221], v[196:199], v[58:61]
	v_mfma_f32_16x16x32_bf16 v[54:57], v[224:227], v[196:199], v[54:57]
	v_mfma_f32_16x16x32_bf16 v[50:53], v[228:231], v[196:199], v[50:53]
	v_mfma_f32_16x16x32_bf16 v[46:49], v[212:215], v[200:203], v[46:49]
	v_mfma_f32_16x16x32_bf16 v[42:45], v[218:221], v[200:203], v[42:45]
	v_mfma_f32_16x16x32_bf16 v[38:41], v[224:227], v[200:203], v[38:41]
	v_mfma_f32_16x16x32_bf16 v[34:37], v[228:231], v[200:203], v[34:37]
	v_mfma_f32_16x16x32_bf16 v[30:33], v[212:215], v[204:207], v[30:33]
	v_mfma_f32_16x16x32_bf16 v[26:29], v[218:221], v[204:207], v[26:29]
	v_mfma_f32_16x16x32_bf16 v[22:25], v[224:227], v[204:207], v[22:25]
	v_mfma_f32_16x16x32_bf16 v[18:21], v[228:231], v[204:207], v[18:21]
	v_mfma_f32_16x16x32_bf16 v[14:17], v[212:215], v[208:211], v[14:17]
	v_mfma_f32_16x16x32_bf16 v[10:13], v[218:221], v[208:211], v[10:13]
	v_mfma_f32_16x16x32_bf16 v[6:9], v[224:227], v[208:211], v[6:9]
	v_mfma_f32_16x16x32_bf16 v[2:5], v[228:231], v[208:211], v[2:5]
	ds_read_b128 v[196:199], v216 offset:8192
	ds_read_b128 v[200:203], v216 offset:10240
	ds_read_b128 v[204:207], v216 offset:12288
	ds_read_b128 v[208:211], v216 offset:14336
	s_waitcnt lgkmcnt(4)
	s_add_u32 s8, s8, 0x80
	s_addc_u32 s9, s9, 0
	s_add_u32 s98, s98, 0x80
	s_addc_u32 s99, s99, 0
	s_add_u32 s100, s100, 0x80
	s_addc_u32 s101, s101, 0
	s_cmpk_eq_i32 s8, 0x780
	s_cbranch_scc1 .Lg2_p4_last
	v_mfma_f32_16x16x32_bf16 v[126:129], v[232:235], v[180:183], v[126:129]
	s_waitcnt vmcnt(7)
	ds_write_b128 v251, v[140:143]
	v_mfma_f32_16x16x32_bf16 v[122:125], v[236:239], v[180:183], v[122:125]
	v_mfma_f32_16x16x32_bf16 v[118:121], v[240:243], v[180:183], v[118:121]
	s_waitcnt vmcnt(6)
	ds_write_b128 v251, v[152:155] offset:8192
	v_add_u32_e32 v142, s15, v248
	v_mfma_f32_16x16x32_bf16 v[114:117], v[244:247], v[180:183], v[114:117]
	global_load_dwordx4 v[140:143], v142, s[98:99] offset:128
	v_mfma_f32_16x16x32_bf16 v[110:113], v[232:235], v[184:187], v[110:113]
	s_waitcnt vmcnt(6)
	ds_write_b128 v251, v[156:159] offset:16384
	v_add_u32_e32 v144, s16, v248
	v_mfma_f32_16x16x32_bf16 v[106:109], v[236:239], v[184:187], v[106:109]
	global_load_dwordx4 v[152:155], v144, s[98:99] offset:128
	v_mfma_f32_16x16x32_bf16 v[102:105], v[240:243], v[184:187], v[102:105]
	s_waitcnt vmcnt(6)
	ds_write_b128 v251, v[160:163] offset:24576
	v_add_u32_e32 v156, s17, v248
	v_mfma_f32_16x16x32_bf16 v[98:101], v[244:247], v[184:187], v[98:101]
	global_load_dwordx4 v[156:159], v156, s[98:99] offset:128
	v_mfma_f32_16x16x32_bf16 v[94:97], v[232:235], v[188:191], v[94:97]
	s_waitcnt vmcnt(6)
	ds_write_b128 v252, v[164:167]
	v_add_u32_e32 v160, s28, v248
	v_mfma_f32_16x16x32_bf16 v[90:93], v[236:239], v[188:191], v[90:93]
	global_load_dwordx4 v[160:163], v160, s[98:99] offset:128
	v_mfma_f32_16x16x32_bf16 v[86:89], v[240:243], v[188:191], v[86:89]
	s_waitcnt vmcnt(6)
	ds_write_b128 v252, v[168:171] offset:8192
	v_add_u32_e32 v164, s29, v250
	v_mfma_f32_16x16x32_bf16 v[82:85], v[244:247], v[188:191], v[82:85]
	global_load_dwordx4 v[164:167], v164, s[100:101] offset:128
	v_mfma_f32_16x16x32_bf16 v[78:81], v[232:235], v[192:195], v[78:81]
	s_waitcnt vmcnt(6)
	ds_write_b128 v252, v[172:175] offset:16384
	v_add_u32_e32 v168, s38, v250
	v_mfma_f32_16x16x32_bf16 v[74:77], v[236:239], v[192:195], v[74:77]
	global_load_dwordx4 v[168:171], v168, s[100:101] offset:128
	v_mfma_f32_16x16x32_bf16 v[70:73], v[240:243], v[192:195], v[70:73]
	s_waitcnt vmcnt(6)
	ds_write_b128 v252, v[176:179] offset:24576
	v_add_u32_e32 v172, s39, v250
	v_mfma_f32_16x16x32_bf16 v[66:69], v[244:247], v[192:195], v[66:69]
	global_load_dwordx4 v[172:175], v172, s[100:101] offset:128
	v_add_u32_e32 v144, s42, v250
	s_nop 0
	global_load_dwordx4 v[176:179], v144, s[100:101] offset:128
	s_waitcnt lgkmcnt(0)
	s_barrier
	v_xor_b32_e32 v223, 0x8000, v223
	v_xor_b32_e32 v249, 0x8000, v249
	v_xor_b32_e32 v216, 0x8000, v216
	v_xor_b32_e32 v217, 0x8000, v217
	v_xor_b32_e32 v251, 0x8000, v251
	v_xor_b32_e32 v252, 0x8000, v252
	ds_read_b128 v[180:183], v223
	ds_read_b128 v[184:187], v223 offset:2048
	ds_read_b128 v[188:191], v223 offset:4096
	ds_read_b128 v[192:195], v223 offset:6144
	ds_read_b128 v[212:215], v249
	ds_read_b128 v[218:221], v249 offset:2048
	ds_read_b128 v[224:227], v249 offset:4096
	ds_read_b128 v[228:231], v249 offset:6144
	v_mfma_f32_16x16x32_bf16 v[62:65], v[232:235], v[196:199], v[62:65]
	v_mfma_f32_16x16x32_bf16 v[58:61], v[236:239], v[196:199], v[58:61]
	v_mfma_f32_16x16x32_bf16 v[54:57], v[240:243], v[196:199], v[54:57]
	v_mfma_f32_16x16x32_bf16 v[50:53], v[244:247], v[196:199], v[50:53]
	v_mfma_f32_16x16x32_bf16 v[46:49], v[232:235], v[200:203], v[46:49]
	v_mfma_f32_16x16x32_bf16 v[42:45], v[236:239], v[200:203], v[42:45]
	v_mfma_f32_16x16x32_bf16 v[38:41], v[240:243], v[200:203], v[38:41]
	v_mfma_f32_16x16x32_bf16 v[34:37], v[244:247], v[200:203], v[34:37]
	v_mfma_f32_16x16x32_bf16 v[30:33], v[232:235], v[204:207], v[30:33]
	v_mfma_f32_16x16x32_bf16 v[26:29], v[236:239], v[204:207], v[26:29]
	v_mfma_f32_16x16x32_bf16 v[22:25], v[240:243], v[204:207], v[22:25]
	v_mfma_f32_16x16x32_bf16 v[18:21], v[244:247], v[204:207], v[18:21]
	v_mfma_f32_16x16x32_bf16 v[14:17], v[232:235], v[208:211], v[14:17]
	v_mfma_f32_16x16x32_bf16 v[10:13], v[236:239], v[208:211], v[10:13]
	v_mfma_f32_16x16x32_bf16 v[6:9], v[240:243], v[208:211], v[6:9]
	v_mfma_f32_16x16x32_bf16 v[2:5], v[244:247], v[208:211], v[2:5]
	s_branch .Lg2_p4_loop
.Lg2_p4_last:
	v_mfma_f32_16x16x32_bf16 v[126:129], v[232:235], v[180:183], v[126:129]
	s_waitcnt vmcnt(7)
	ds_write_b128 v251, v[140:143]
	v_mfma_f32_16x16x32_bf16 v[122:125], v[236:239], v[180:183], v[122:125]
	v_mfma_f32_16x16x32_bf16 v[118:121], v[240:243], v[180:183], v[118:121]
	s_waitcnt vmcnt(6)
	ds_write_b128 v251, v[152:155] offset:8192
	v_mfma_f32_16x16x32_bf16 v[114:117], v[244:247], v[180:183], v[114:117]
	v_mfma_f32_16x16x32_bf16 v[110:113], v[232:235], v[184:187], v[110:113]
	s_waitcnt vmcnt(5)
	ds_write_b128 v251, v[156:159] offset:16384
	v_mfma_f32_16x16x32_bf16 v[106:109], v[236:239], v[184:187], v[106:109]
	v_mfma_f32_16x16x32_bf16 v[102:105], v[240:243], v[184:187], v[102:105]
	s_waitcnt vmcnt(4)
	ds_write_b128 v251, v[160:163] offset:24576
	v_mfma_f32_16x16x32_bf16 v[98:101], v[244:247], v[184:187], v[98:101]
	v_mfma_f32_16x16x32_bf16 v[94:97], v[232:235], v[188:191], v[94:97]
	s_waitcnt vmcnt(3)
	ds_write_b128 v252, v[164:167]
	v_mfma_f32_16x16x32_bf16 v[90:93], v[236:239], v[188:191], v[90:93]
	v_mfma_f32_16x16x32_bf16 v[86:89], v[240:243], v[188:191], v[86:89]
	s_waitcnt vmcnt(2)
	ds_write_b128 v252, v[168:171] offset:8192
	v_mfma_f32_16x16x32_bf16 v[82:85], v[244:247], v[188:191], v[82:85]
	v_mfma_f32_16x16x32_bf16 v[78:81], v[232:235], v[192:195], v[78:81]
	s_waitcnt vmcnt(1)
	ds_write_b128 v252, v[172:175] offset:16384
	v_mfma_f32_16x16x32_bf16 v[74:77], v[236:239], v[192:195], v[74:77]
	v_mfma_f32_16x16x32_bf16 v[70:73], v[240:243], v[192:195], v[70:73]
	s_waitcnt vmcnt(0)
	ds_write_b128 v252, v[176:179] offset:24576
	v_mfma_f32_16x16x32_bf16 v[66:69], v[244:247], v[192:195], v[66:69]
	s_waitcnt lgkmcnt(0)
	s_barrier

.Lg2_p6_loop:
	ds_read_b128 v[198:201], v214 offset:8192
	ds_read_b128 v[202:205], v214 offset:10240
	ds_read_b128 v[206:209], v214 offset:12288
	ds_read_b128 v[210:213], v214 offset:14336
	s_waitcnt lgkmcnt(4)
	v_mfma_f32_16x16x32_bf16 v[126:129], v[218:221], v[182:185], v[126:129]
	v_mfma_f32_16x16x32_bf16 v[122:125], v[224:227], v[182:185], v[122:125]
	v_mfma_f32_16x16x32_bf16 v[118:121], v[228:231], v[182:185], v[118:121]
	v_mfma_f32_16x16x32_bf16 v[114:117], v[232:235], v[182:185], v[114:117]
	v_mfma_f32_16x16x32_bf16 v[110:113], v[218:221], v[186:189], v[110:113]
	v_mfma_f32_16x16x32_bf16 v[106:109], v[224:227], v[186:189], v[106:109]
	v_mfma_f32_16x16x32_bf16 v[102:105], v[228:231], v[186:189], v[102:105]
	v_mfma_f32_16x16x32_bf16 v[98:101], v[232:235], v[186:189], v[98:101]
	v_mfma_f32_16x16x32_bf16 v[94:97], v[218:221], v[190:193], v[94:97]
	v_mfma_f32_16x16x32_bf16 v[90:93], v[224:227], v[190:193], v[90:93]
	v_mfma_f32_16x16x32_bf16 v[86:89], v[228:231], v[190:193], v[86:89]
	v_mfma_f32_16x16x32_bf16 v[82:85], v[232:235], v[190:193], v[82:85]
	v_mfma_f32_16x16x32_bf16 v[78:81], v[218:221], v[194:197], v[78:81]
	v_mfma_f32_16x16x32_bf16 v[74:77], v[224:227], v[194:197], v[74:77]
	v_mfma_f32_16x16x32_bf16 v[70:73], v[228:231], v[194:197], v[70:73]
	v_mfma_f32_16x16x32_bf16 v[66:69], v[232:235], v[194:197], v[66:69]
	ds_read_b128 v[182:185], v216
	ds_read_b128 v[186:189], v216 offset:2048
	ds_read_b128 v[190:193], v216 offset:4096
	ds_read_b128 v[194:197], v216 offset:6144
	ds_read_b128 v[236:239], v217
	ds_read_b128 v[240:243], v217 offset:2048
	ds_read_b128 v[244:247], v217 offset:4096
	ds_read_b128 v[248:251], v217 offset:6144
	s_waitcnt lgkmcnt(8)
	v_mfma_f32_16x16x32_bf16 v[62:65], v[218:221], v[198:201], v[62:65]
	v_mfma_f32_16x16x32_bf16 v[58:61], v[224:227], v[198:201], v[58:61]
	v_mfma_f32_16x16x32_bf16 v[54:57], v[228:231], v[198:201], v[54:57]
	v_mfma_f32_16x16x32_bf16 v[50:53], v[232:235], v[198:201], v[50:53]
	v_mfma_f32_16x16x32_bf16 v[46:49], v[218:221], v[202:205], v[46:49]
	v_mfma_f32_16x16x32_bf16 v[42:45], v[224:227], v[202:205], v[42:45]
	v_mfma_f32_16x16x32_bf16 v[38:41], v[228:231], v[202:205], v[38:41]
	v_mfma_f32_16x16x32_bf16 v[34:37], v[232:235], v[202:205], v[34:37]
	v_mfma_f32_16x16x32_bf16 v[30:33], v[218:221], v[206:209], v[30:33]
	v_mfma_f32_16x16x32_bf16 v[26:29], v[224:227], v[206:209], v[26:29]
	v_mfma_f32_16x16x32_bf16 v[22:25], v[228:231], v[206:209], v[22:25]
	v_mfma_f32_16x16x32_bf16 v[18:21], v[232:235], v[206:209], v[18:21]
	v_mfma_f32_16x16x32_bf16 v[14:17], v[218:221], v[210:213], v[14:17]
	v_mfma_f32_16x16x32_bf16 v[10:13], v[224:227], v[210:213], v[10:13]
	v_mfma_f32_16x16x32_bf16 v[6:9], v[228:231], v[210:213], v[6:9]
	v_mfma_f32_16x16x32_bf16 v[2:5], v[232:235], v[210:213], v[2:5]
	ds_read_b128 v[198:201], v216 offset:8192
	ds_read_b128 v[202:205], v216 offset:10240
	ds_read_b128 v[206:209], v216 offset:12288
	ds_read_b128 v[210:213], v216 offset:14336
	s_waitcnt lgkmcnt(4)
	s_add_u32 s0, s0, 0x80
	s_addc_u32 s1, s1, 0
	s_add_u32 s98, s98, 0x80
	s_addc_u32 s99, s99, 0
	s_add_u32 s100, s100, 0x80
	s_addc_u32 s101, s101, 0
	s_cmpk_eq_i32 s0, 0x780
	s_cbranch_scc1 .Lg2_p6_last
	v_mfma_f32_16x16x32_bf16 v[126:129], v[236:239], v[182:185], v[126:129]
	s_waitcnt vmcnt(7)
	ds_write_b128 v253, v[150:153]
	v_mfma_f32_16x16x32_bf16 v[122:125], v[240:243], v[182:185], v[122:125]
	v_mfma_f32_16x16x32_bf16 v[118:121], v[244:247], v[182:185], v[118:121]
	s_waitcnt vmcnt(6)
	ds_write_b128 v253, v[154:157] offset:8192
	v_add_u32_e32 v152, s12, v215
	v_mfma_f32_16x16x32_bf16 v[114:117], v[248:251], v[182:185], v[114:117]
	global_load_dwordx4 v[150:153], v152, s[98:99] offset:128
	v_mfma_f32_16x16x32_bf16 v[110:113], v[236:239], v[186:189], v[110:113]
	s_waitcnt vmcnt(6)
	ds_write_b128 v253, v[158:161] offset:16384
	v_add_u32_e32 v154, s13, v215
	v_mfma_f32_16x16x32_bf16 v[106:109], v[240:243], v[186:189], v[106:109]
	global_load_dwordx4 v[154:157], v154, s[98:99] offset:128
	v_mfma_f32_16x16x32_bf16 v[102:105], v[244:247], v[186:189], v[102:105]
	s_waitcnt vmcnt(6)
	ds_write_b128 v253, v[162:165] offset:24576
	v_add_u32_e32 v158, s14, v215
	v_mfma_f32_16x16x32_bf16 v[98:101], v[248:251], v[186:189], v[98:101]
	global_load_dwordx4 v[158:161], v158, s[98:99] offset:128
	v_mfma_f32_16x16x32_bf16 v[94:97], v[236:239], v[190:193], v[94:97]
	s_waitcnt vmcnt(6)
	ds_write_b128 v254, v[166:169]
	v_add_u32_e32 v162, s15, v215
	v_mfma_f32_16x16x32_bf16 v[90:93], v[240:243], v[190:193], v[90:93]
	global_load_dwordx4 v[162:165], v162, s[98:99] offset:128
	v_mfma_f32_16x16x32_bf16 v[86:89], v[244:247], v[190:193], v[86:89]
	s_waitcnt vmcnt(6)
	ds_write_b128 v254, v[170:173] offset:8192
	v_add_u32_e32 v166, s16, v252
	v_mfma_f32_16x16x32_bf16 v[82:85], v[248:251], v[190:193], v[82:85]
	global_load_dwordx4 v[166:169], v166, s[100:101] offset:128
	v_mfma_f32_16x16x32_bf16 v[78:81], v[236:239], v[194:197], v[78:81]
	s_waitcnt vmcnt(6)
	ds_write_b128 v254, v[174:177] offset:16384
	v_add_u32_e32 v170, s17, v252
	v_mfma_f32_16x16x32_bf16 v[74:77], v[240:243], v[194:197], v[74:77]
	global_load_dwordx4 v[170:173], v170, s[100:101] offset:128
	v_mfma_f32_16x16x32_bf16 v[70:73], v[244:247], v[194:197], v[70:73]
	s_waitcnt vmcnt(6)
	ds_write_b128 v254, v[178:181] offset:24576
	v_add_u32_e32 v176, s28, v252
	v_mfma_f32_16x16x32_bf16 v[66:69], v[248:251], v[194:197], v[66:69]
	global_load_dwordx4 v[174:177], v176, s[100:101] offset:128
	v_add_u32_e32 v178, s29, v252
	s_nop 0
	global_load_dwordx4 v[178:181], v178, s[100:101] offset:128
	s_waitcnt lgkmcnt(0)
	s_barrier
	v_xor_b32_e32 v214, 0x8000, v214
	v_xor_b32_e32 v223, 0x8000, v223
	v_xor_b32_e32 v216, 0x8000, v216
	v_xor_b32_e32 v217, 0x8000, v217
	v_xor_b32_e32 v253, 0x8000, v253
	v_xor_b32_e32 v254, 0x8000, v254
	ds_read_b128 v[182:185], v214
	ds_read_b128 v[186:189], v214 offset:2048
	ds_read_b128 v[190:193], v214 offset:4096
	ds_read_b128 v[194:197], v214 offset:6144
	ds_read_b128 v[218:221], v223
	ds_read_b128 v[224:227], v223 offset:2048
	ds_read_b128 v[228:231], v223 offset:4096
	ds_read_b128 v[232:235], v223 offset:6144
	v_mfma_f32_16x16x32_bf16 v[62:65], v[236:239], v[198:201], v[62:65]
	v_mfma_f32_16x16x32_bf16 v[58:61], v[240:243], v[198:201], v[58:61]
	v_mfma_f32_16x16x32_bf16 v[54:57], v[244:247], v[198:201], v[54:57]
	v_mfma_f32_16x16x32_bf16 v[50:53], v[248:251], v[198:201], v[50:53]
	v_mfma_f32_16x16x32_bf16 v[46:49], v[236:239], v[202:205], v[46:49]
	v_mfma_f32_16x16x32_bf16 v[42:45], v[240:243], v[202:205], v[42:45]
	v_mfma_f32_16x16x32_bf16 v[38:41], v[244:247], v[202:205], v[38:41]
	v_mfma_f32_16x16x32_bf16 v[34:37], v[248:251], v[202:205], v[34:37]
	v_mfma_f32_16x16x32_bf16 v[30:33], v[236:239], v[206:209], v[30:33]
	v_mfma_f32_16x16x32_bf16 v[26:29], v[240:243], v[206:209], v[26:29]
	v_mfma_f32_16x16x32_bf16 v[22:25], v[244:247], v[206:209], v[22:25]
	v_mfma_f32_16x16x32_bf16 v[18:21], v[248:251], v[206:209], v[18:21]
	v_mfma_f32_16x16x32_bf16 v[14:17], v[236:239], v[210:213], v[14:17]
	v_mfma_f32_16x16x32_bf16 v[10:13], v[240:243], v[210:213], v[10:13]
	v_mfma_f32_16x16x32_bf16 v[6:9], v[244:247], v[210:213], v[6:9]
	v_mfma_f32_16x16x32_bf16 v[2:5], v[248:251], v[210:213], v[2:5]
	s_branch .Lg2_p6_loop
.Lg2_p6_last:
	v_mfma_f32_16x16x32_bf16 v[126:129], v[236:239], v[182:185], v[126:129]
	s_waitcnt vmcnt(7)
	ds_write_b128 v253, v[150:153]
	v_mfma_f32_16x16x32_bf16 v[122:125], v[240:243], v[182:185], v[122:125]
	v_mfma_f32_16x16x32_bf16 v[118:121], v[244:247], v[182:185], v[118:121]
	s_waitcnt vmcnt(6)
	ds_write_b128 v253, v[154:157] offset:8192
	v_mfma_f32_16x16x32_bf16 v[114:117], v[248:251], v[182:185], v[114:117]
	v_mfma_f32_16x16x32_bf16 v[110:113], v[236:239], v[186:189], v[110:113]
	s_waitcnt vmcnt(5)
	ds_write_b128 v253, v[158:161] offset:16384
	v_mfma_f32_16x16x32_bf16 v[106:109], v[240:243], v[186:189], v[106:109]
	v_mfma_f32_16x16x32_bf16 v[102:105], v[244:247], v[186:189], v[102:105]
	s_waitcnt vmcnt(4)
	ds_write_b128 v253, v[162:165] offset:24576
	v_mfma_f32_16x16x32_bf16 v[98:101], v[248:251], v[186:189], v[98:101]
	v_mfma_f32_16x16x32_bf16 v[94:97], v[236:239], v[190:193], v[94:97]
	s_waitcnt vmcnt(3)
	ds_write_b128 v254, v[166:169]
	v_mfma_f32_16x16x32_bf16 v[90:93], v[240:243], v[190:193], v[90:93]
	v_mfma_f32_16x16x32_bf16 v[86:89], v[244:247], v[190:193], v[86:89]
	s_waitcnt vmcnt(2)
	ds_write_b128 v254, v[170:173] offset:8192
	v_mfma_f32_16x16x32_bf16 v[82:85], v[248:251], v[190:193], v[82:85]
	v_mfma_f32_16x16x32_bf16 v[78:81], v[236:239], v[194:197], v[78:81]
	s_waitcnt vmcnt(1)
	ds_write_b128 v254, v[174:177] offset:16384
	v_mfma_f32_16x16x32_bf16 v[74:77], v[240:243], v[194:197], v[74:77]
	v_mfma_f32_16x16x32_bf16 v[70:73], v[244:247], v[194:197], v[70:73]
	s_waitcnt vmcnt(0)
	ds_write_b128 v254, v[178:181] offset:24576
	v_mfma_f32_16x16x32_bf16 v[66:69], v[248:251], v[194:197], v[66:69]
	s_waitcnt lgkmcnt(0)
	s_barrier

.Lg2_p7_loop:
	ds_read_b128 v[196:199], v223 offset:8192
	ds_read_b128 v[200:203], v223 offset:10240
	ds_read_b128 v[204:207], v223 offset:12288
	ds_read_b128 v[208:211], v223 offset:14336
	s_waitcnt lgkmcnt(4)
	v_mfma_f32_16x16x32_bf16 v[126:129], v[212:215], v[180:183], v[126:129]
	v_mfma_f32_16x16x32_bf16 v[122:125], v[218:221], v[180:183], v[122:125]
	v_mfma_f32_16x16x32_bf16 v[118:121], v[224:227], v[180:183], v[118:121]
	v_mfma_f32_16x16x32_bf16 v[114:117], v[228:231], v[180:183], v[114:117]
	v_mfma_f32_16x16x32_bf16 v[110:113], v[212:215], v[184:187], v[110:113]
	v_mfma_f32_16x16x32_bf16 v[106:109], v[218:221], v[184:187], v[106:109]
	v_mfma_f32_16x16x32_bf16 v[102:105], v[224:227], v[184:187], v[102:105]
	v_mfma_f32_16x16x32_bf16 v[98:101], v[228:231], v[184:187], v[98:101]
	v_mfma_f32_16x16x32_bf16 v[94:97], v[212:215], v[188:191], v[94:97]
	v_mfma_f32_16x16x32_bf16 v[90:93], v[218:221], v[188:191], v[90:93]
	v_mfma_f32_16x16x32_bf16 v[86:89], v[224:227], v[188:191], v[86:89]
	v_mfma_f32_16x16x32_bf16 v[82:85], v[228:231], v[188:191], v[82:85]
	v_mfma_f32_16x16x32_bf16 v[78:81], v[212:215], v[192:195], v[78:81]
	v_mfma_f32_16x16x32_bf16 v[74:77], v[218:221], v[192:195], v[74:77]
	v_mfma_f32_16x16x32_bf16 v[70:73], v[224:227], v[192:195], v[70:73]
	v_mfma_f32_16x16x32_bf16 v[66:69], v[228:231], v[192:195], v[66:69]
	ds_read_b128 v[180:183], v216
	ds_read_b128 v[184:187], v216 offset:2048
	ds_read_b128 v[188:191], v216 offset:4096
	ds_read_b128 v[192:195], v216 offset:6144
	ds_read_b128 v[232:235], v217
	ds_read_b128 v[236:239], v217 offset:2048
	ds_read_b128 v[240:243], v217 offset:4096
	ds_read_b128 v[244:247], v217 offset:6144
	s_waitcnt lgkmcnt(8)
	v_mfma_f32_16x16x32_bf16 v[62:65], v[212:215], v[196:199], v[62:65]
	v_mfma_f32_16x16x32_bf16 v[58:61], v[218:221], v[196:199], v[58:61]
	v_mfma_f32_16x16x32_bf16 v[54:57], v[224:227], v[196:199], v[54:57]
	v_mfma_f32_16x16x32_bf16 v[50:53], v[228:231], v[196:199], v[50:53]
	v_mfma_f32_16x16x32_bf16 v[46:49], v[212:215], v[200:203], v[46:49]
	v_mfma_f32_16x16x32_bf16 v[42:45], v[218:221], v[200:203], v[42:45]
	v_mfma_f32_16x16x32_bf16 v[38:41], v[224:227], v[200:203], v[38:41]
	v_mfma_f32_16x16x32_bf16 v[34:37], v[228:231], v[200:203], v[34:37]
	v_mfma_f32_16x16x32_bf16 v[30:33], v[212:215], v[204:207], v[30:33]
	v_mfma_f32_16x16x32_bf16 v[26:29], v[218:221], v[204:207], v[26:29]
	v_mfma_f32_16x16x32_bf16 v[22:25], v[224:227], v[204:207], v[22:25]
	v_mfma_f32_16x16x32_bf16 v[18:21], v[228:231], v[204:207], v[18:21]
	v_mfma_f32_16x16x32_bf16 v[14:17], v[212:215], v[208:211], v[14:17]
	v_mfma_f32_16x16x32_bf16 v[10:13], v[218:221], v[208:211], v[10:13]
	v_mfma_f32_16x16x32_bf16 v[6:9], v[224:227], v[208:211], v[6:9]
	v_mfma_f32_16x16x32_bf16 v[2:5], v[228:231], v[208:211], v[2:5]
	ds_read_b128 v[196:199], v216 offset:8192
	ds_read_b128 v[200:203], v216 offset:10240
	ds_read_b128 v[204:207], v216 offset:12288
	ds_read_b128 v[208:211], v216 offset:14336
	s_waitcnt lgkmcnt(4)
	s_add_u32 s8, s8, 0x80
	s_addc_u32 s9, s9, 0
	s_add_u32 s98, s98, 0x80
	s_addc_u32 s99, s99, 0
	s_add_u32 s100, s100, 0x80
	s_addc_u32 s101, s101, 0
	s_cmpk_eq_i32 s8, 0x1580
	s_cbranch_scc1 .Lg2_p7_last
	v_mfma_f32_16x16x32_bf16 v[126:129], v[232:235], v[180:183], v[126:129]
	s_waitcnt vmcnt(7)
	ds_write_b128 v251, v[140:143]
	v_mfma_f32_16x16x32_bf16 v[122:125], v[236:239], v[180:183], v[122:125]
	v_mfma_f32_16x16x32_bf16 v[118:121], v[240:243], v[180:183], v[118:121]
	s_waitcnt vmcnt(6)
	ds_write_b128 v251, v[152:155] offset:8192
	v_add_u32_e32 v142, s16, v248
	v_mfma_f32_16x16x32_bf16 v[114:117], v[244:247], v[180:183], v[114:117]
	global_load_dwordx4 v[140:143], v142, s[98:99] offset:128
	v_mfma_f32_16x16x32_bf16 v[110:113], v[232:235], v[184:187], v[110:113]
	s_waitcnt vmcnt(6)
	ds_write_b128 v251, v[156:159] offset:16384
	v_add_u32_e32 v144, s17, v248
	v_mfma_f32_16x16x32_bf16 v[106:109], v[236:239], v[184:187], v[106:109]
	global_load_dwordx4 v[152:155], v144, s[98:99] offset:128
	v_mfma_f32_16x16x32_bf16 v[102:105], v[240:243], v[184:187], v[102:105]
	s_waitcnt vmcnt(6)
	ds_write_b128 v251, v[160:163] offset:24576
	v_add_u32_e32 v156, s28, v248
	v_mfma_f32_16x16x32_bf16 v[98:101], v[244:247], v[184:187], v[98:101]
	global_load_dwordx4 v[156:159], v156, s[98:99] offset:128
	v_mfma_f32_16x16x32_bf16 v[94:97], v[232:235], v[188:191], v[94:97]
	s_waitcnt vmcnt(6)
	ds_write_b128 v252, v[164:167]
	v_add_u32_e32 v160, s29, v248
	v_mfma_f32_16x16x32_bf16 v[90:93], v[236:239], v[188:191], v[90:93]
	global_load_dwordx4 v[160:163], v160, s[98:99] offset:128
	v_mfma_f32_16x16x32_bf16 v[86:89], v[240:243], v[188:191], v[86:89]
	s_waitcnt vmcnt(6)
	ds_write_b128 v252, v[168:171] offset:8192
	v_add_u32_e32 v164, s36, v250
	v_mfma_f32_16x16x32_bf16 v[82:85], v[244:247], v[188:191], v[82:85]
	global_load_dwordx4 v[164:167], v164, s[100:101] offset:128
	v_mfma_f32_16x16x32_bf16 v[78:81], v[232:235], v[192:195], v[78:81]
	s_waitcnt vmcnt(6)
	ds_write_b128 v252, v[172:175] offset:16384
	v_add_u32_e32 v168, s37, v250
	v_mfma_f32_16x16x32_bf16 v[74:77], v[236:239], v[192:195], v[74:77]
	global_load_dwordx4 v[168:171], v168, s[100:101] offset:128
	v_mfma_f32_16x16x32_bf16 v[70:73], v[240:243], v[192:195], v[70:73]
	s_waitcnt vmcnt(6)
	ds_write_b128 v252, v[176:179] offset:24576
	v_add_u32_e32 v172, s38, v250
	v_mfma_f32_16x16x32_bf16 v[66:69], v[244:247], v[192:195], v[66:69]
	global_load_dwordx4 v[172:175], v172, s[100:101] offset:128
	v_add_u32_e32 v144, s39, v250
	s_nop 0
	global_load_dwordx4 v[176:179], v144, s[100:101] offset:128
	s_waitcnt lgkmcnt(0)
	s_barrier
	v_xor_b32_e32 v223, 0x8000, v223
	v_xor_b32_e32 v249, 0x8000, v249
	v_xor_b32_e32 v216, 0x8000, v216
	v_xor_b32_e32 v217, 0x8000, v217
	v_xor_b32_e32 v251, 0x8000, v251
	v_xor_b32_e32 v252, 0x8000, v252
	ds_read_b128 v[180:183], v223
	ds_read_b128 v[184:187], v223 offset:2048
	ds_read_b128 v[188:191], v223 offset:4096
	ds_read_b128 v[192:195], v223 offset:6144
	ds_read_b128 v[212:215], v249
	ds_read_b128 v[218:221], v249 offset:2048
	ds_read_b128 v[224:227], v249 offset:4096
	ds_read_b128 v[228:231], v249 offset:6144
	v_mfma_f32_16x16x32_bf16 v[62:65], v[232:235], v[196:199], v[62:65]
	v_mfma_f32_16x16x32_bf16 v[58:61], v[236:239], v[196:199], v[58:61]
	v_mfma_f32_16x16x32_bf16 v[54:57], v[240:243], v[196:199], v[54:57]
	v_mfma_f32_16x16x32_bf16 v[50:53], v[244:247], v[196:199], v[50:53]
	v_mfma_f32_16x16x32_bf16 v[46:49], v[232:235], v[200:203], v[46:49]
	v_mfma_f32_16x16x32_bf16 v[42:45], v[236:239], v[200:203], v[42:45]
	v_mfma_f32_16x16x32_bf16 v[38:41], v[240:243], v[200:203], v[38:41]
	v_mfma_f32_16x16x32_bf16 v[34:37], v[244:247], v[200:203], v[34:37]
	v_mfma_f32_16x16x32_bf16 v[30:33], v[232:235], v[204:207], v[30:33]
	v_mfma_f32_16x16x32_bf16 v[26:29], v[236:239], v[204:207], v[26:29]
	v_mfma_f32_16x16x32_bf16 v[22:25], v[240:243], v[204:207], v[22:25]
	v_mfma_f32_16x16x32_bf16 v[18:21], v[244:247], v[204:207], v[18:21]
	v_mfma_f32_16x16x32_bf16 v[14:17], v[232:235], v[208:211], v[14:17]
	v_mfma_f32_16x16x32_bf16 v[10:13], v[236:239], v[208:211], v[10:13]
	v_mfma_f32_16x16x32_bf16 v[6:9], v[240:243], v[208:211], v[6:9]
	v_mfma_f32_16x16x32_bf16 v[2:5], v[244:247], v[208:211], v[2:5]
	s_branch .Lg2_p7_loop

.Lg2_p12_loop:
	ds_read_b128 v[196:199], v223 offset:8192
	ds_read_b128 v[200:203], v223 offset:10240
	ds_read_b128 v[204:207], v223 offset:12288
	ds_read_b128 v[208:211], v223 offset:14336
	s_waitcnt lgkmcnt(4)
	v_mfma_f32_16x16x32_bf16 v[126:129], v[212:215], v[180:183], v[126:129]
	v_mfma_f32_16x16x32_bf16 v[122:125], v[218:221], v[180:183], v[122:125]
	v_mfma_f32_16x16x32_bf16 v[118:121], v[224:227], v[180:183], v[118:121]
	v_mfma_f32_16x16x32_bf16 v[114:117], v[228:231], v[180:183], v[114:117]
	v_mfma_f32_16x16x32_bf16 v[110:113], v[212:215], v[184:187], v[110:113]
	v_mfma_f32_16x16x32_bf16 v[106:109], v[218:221], v[184:187], v[106:109]
	v_mfma_f32_16x16x32_bf16 v[102:105], v[224:227], v[184:187], v[102:105]
	v_mfma_f32_16x16x32_bf16 v[98:101], v[228:231], v[184:187], v[98:101]
	v_mfma_f32_16x16x32_bf16 v[94:97], v[212:215], v[188:191], v[94:97]
	v_mfma_f32_16x16x32_bf16 v[90:93], v[218:221], v[188:191], v[90:93]
	v_mfma_f32_16x16x32_bf16 v[86:89], v[224:227], v[188:191], v[86:89]
	v_mfma_f32_16x16x32_bf16 v[82:85], v[228:231], v[188:191], v[82:85]
	v_mfma_f32_16x16x32_bf16 v[78:81], v[212:215], v[192:195], v[78:81]
	v_mfma_f32_16x16x32_bf16 v[74:77], v[218:221], v[192:195], v[74:77]
	v_mfma_f32_16x16x32_bf16 v[70:73], v[224:227], v[192:195], v[70:73]
	v_mfma_f32_16x16x32_bf16 v[66:69], v[228:231], v[192:195], v[66:69]
	ds_read_b128 v[180:183], v216
	ds_read_b128 v[184:187], v216 offset:2048
	ds_read_b128 v[188:191], v216 offset:4096
	ds_read_b128 v[192:195], v216 offset:6144
	ds_read_b128 v[232:235], v217
	ds_read_b128 v[236:239], v217 offset:2048
	ds_read_b128 v[240:243], v217 offset:4096
	ds_read_b128 v[244:247], v217 offset:6144
	s_waitcnt lgkmcnt(8)
	v_mfma_f32_16x16x32_bf16 v[62:65], v[212:215], v[196:199], v[62:65]
	v_mfma_f32_16x16x32_bf16 v[58:61], v[218:221], v[196:199], v[58:61]
	v_mfma_f32_16x16x32_bf16 v[54:57], v[224:227], v[196:199], v[54:57]
	v_mfma_f32_16x16x32_bf16 v[50:53], v[228:231], v[196:199], v[50:53]
	v_mfma_f32_16x16x32_bf16 v[46:49], v[212:215], v[200:203], v[46:49]
	v_mfma_f32_16x16x32_bf16 v[42:45], v[218:221], v[200:203], v[42:45]
	v_mfma_f32_16x16x32_bf16 v[38:41], v[224:227], v[200:203], v[38:41]
	v_mfma_f32_16x16x32_bf16 v[34:37], v[228:231], v[200:203], v[34:37]
	v_mfma_f32_16x16x32_bf16 v[30:33], v[212:215], v[204:207], v[30:33]
	v_mfma_f32_16x16x32_bf16 v[26:29], v[218:221], v[204:207], v[26:29]
	v_mfma_f32_16x16x32_bf16 v[22:25], v[224:227], v[204:207], v[22:25]
	v_mfma_f32_16x16x32_bf16 v[18:21], v[228:231], v[204:207], v[18:21]
	v_mfma_f32_16x16x32_bf16 v[14:17], v[212:215], v[208:211], v[14:17]
	v_mfma_f32_16x16x32_bf16 v[10:13], v[218:221], v[208:211], v[10:13]
	v_mfma_f32_16x16x32_bf16 v[6:9], v[224:227], v[208:211], v[6:9]
	v_mfma_f32_16x16x32_bf16 v[2:5], v[228:231], v[208:211], v[2:5]
	ds_read_b128 v[196:199], v216 offset:8192
	ds_read_b128 v[200:203], v216 offset:10240
	ds_read_b128 v[204:207], v216 offset:12288
	ds_read_b128 v[208:211], v216 offset:14336
	s_waitcnt lgkmcnt(4)
	s_add_u32 s8, s8, 0x80
	s_addc_u32 s9, s9, 0
	s_add_u32 s98, s98, 0x80
	s_addc_u32 s99, s99, 0
	s_add_u32 s100, s100, 0x80
	s_addc_u32 s101, s101, 0
	s_cmpk_eq_i32 s8, 0x780
	s_cbranch_scc1 .Lg2_p12_last
	v_mfma_f32_16x16x32_bf16 v[126:129], v[232:235], v[180:183], v[126:129]
	s_waitcnt vmcnt(7)
	ds_write_b128 v251, v[140:143]
	v_mfma_f32_16x16x32_bf16 v[122:125], v[236:239], v[180:183], v[122:125]
	v_mfma_f32_16x16x32_bf16 v[118:121], v[240:243], v[180:183], v[118:121]
	s_waitcnt vmcnt(6)
	ds_write_b128 v251, v[152:155] offset:8192
	v_add_u32_e32 v142, s15, v248
	v_mfma_f32_16x16x32_bf16 v[114:117], v[244:247], v[180:183], v[114:117]
	global_load_dwordx4 v[140:143], v142, s[98:99] offset:128
	v_mfma_f32_16x16x32_bf16 v[110:113], v[232:235], v[184:187], v[110:113]
	s_waitcnt vmcnt(6)
	ds_write_b128 v251, v[156:159] offset:16384
	v_add_u32_e32 v144, s16, v248
	v_mfma_f32_16x16x32_bf16 v[106:109], v[236:239], v[184:187], v[106:109]
	global_load_dwordx4 v[152:155], v144, s[98:99] offset:128
	v_mfma_f32_16x16x32_bf16 v[102:105], v[240:243], v[184:187], v[102:105]
	s_waitcnt vmcnt(6)
	ds_write_b128 v251, v[160:163] offset:24576
	v_add_u32_e32 v156, s17, v248
	v_mfma_f32_16x16x32_bf16 v[98:101], v[244:247], v[184:187], v[98:101]
	global_load_dwordx4 v[156:159], v156, s[98:99] offset:128
	v_mfma_f32_16x16x32_bf16 v[94:97], v[232:235], v[188:191], v[94:97]
	s_waitcnt vmcnt(6)
	ds_write_b128 v252, v[164:167]
	v_add_u32_e32 v160, s18, v248
	v_mfma_f32_16x16x32_bf16 v[90:93], v[236:239], v[188:191], v[90:93]
	global_load_dwordx4 v[160:163], v160, s[98:99] offset:128
	v_mfma_f32_16x16x32_bf16 v[86:89], v[240:243], v[188:191], v[86:89]
	s_waitcnt vmcnt(6)
	ds_write_b128 v252, v[168:171] offset:8192
	v_add_u32_e32 v164, s19, v250
	v_mfma_f32_16x16x32_bf16 v[82:85], v[244:247], v[188:191], v[82:85]
	global_load_dwordx4 v[164:167], v164, s[100:101] offset:128
	v_mfma_f32_16x16x32_bf16 v[78:81], v[232:235], v[192:195], v[78:81]
	s_waitcnt vmcnt(6)
	ds_write_b128 v252, v[172:175] offset:16384
	v_add_u32_e32 v168, s20, v250
	v_mfma_f32_16x16x32_bf16 v[74:77], v[236:239], v[192:195], v[74:77]
	global_load_dwordx4 v[168:171], v168, s[100:101] offset:128
	v_mfma_f32_16x16x32_bf16 v[70:73], v[240:243], v[192:195], v[70:73]
	s_waitcnt vmcnt(6)
	ds_write_b128 v252, v[176:179] offset:24576
	v_add_u32_e32 v172, s21, v250
	v_mfma_f32_16x16x32_bf16 v[66:69], v[244:247], v[192:195], v[66:69]
	global_load_dwordx4 v[172:175], v172, s[100:101] offset:128
	v_add_u32_e32 v144, s22, v250
	s_nop 0
	global_load_dwordx4 v[176:179], v144, s[100:101] offset:128
	s_waitcnt lgkmcnt(0)
	s_barrier
	v_xor_b32_e32 v223, 0x8000, v223
	v_xor_b32_e32 v249, 0x8000, v249
	v_xor_b32_e32 v216, 0x8000, v216
	v_xor_b32_e32 v217, 0x8000, v217
	v_xor_b32_e32 v251, 0x8000, v251
	v_xor_b32_e32 v252, 0x8000, v252
	ds_read_b128 v[180:183], v223
	ds_read_b128 v[184:187], v223 offset:2048
	ds_read_b128 v[188:191], v223 offset:4096
	ds_read_b128 v[192:195], v223 offset:6144
	ds_read_b128 v[212:215], v249
	ds_read_b128 v[218:221], v249 offset:2048
	ds_read_b128 v[224:227], v249 offset:4096
	ds_read_b128 v[228:231], v249 offset:6144
	v_mfma_f32_16x16x32_bf16 v[62:65], v[232:235], v[196:199], v[62:65]
	v_mfma_f32_16x16x32_bf16 v[58:61], v[236:239], v[196:199], v[58:61]
	v_mfma_f32_16x16x32_bf16 v[54:57], v[240:243], v[196:199], v[54:57]
	v_mfma_f32_16x16x32_bf16 v[50:53], v[244:247], v[196:199], v[50:53]
	v_mfma_f32_16x16x32_bf16 v[46:49], v[232:235], v[200:203], v[46:49]
	v_mfma_f32_16x16x32_bf16 v[42:45], v[236:239], v[200:203], v[42:45]
	v_mfma_f32_16x16x32_bf16 v[38:41], v[240:243], v[200:203], v[38:41]
	v_mfma_f32_16x16x32_bf16 v[34:37], v[244:247], v[200:203], v[34:37]
	v_mfma_f32_16x16x32_bf16 v[30:33], v[232:235], v[204:207], v[30:33]
	v_mfma_f32_16x16x32_bf16 v[26:29], v[236:239], v[204:207], v[26:29]
	v_mfma_f32_16x16x32_bf16 v[22:25], v[240:243], v[204:207], v[22:25]
	v_mfma_f32_16x16x32_bf16 v[18:21], v[244:247], v[204:207], v[18:21]
	v_mfma_f32_16x16x32_bf16 v[14:17], v[232:235], v[208:211], v[14:17]
	v_mfma_f32_16x16x32_bf16 v[10:13], v[236:239], v[208:211], v[10:13]
	v_mfma_f32_16x16x32_bf16 v[6:9], v[240:243], v[208:211], v[6:9]
	v_mfma_f32_16x16x32_bf16 v[2:5], v[244:247], v[208:211], v[2:5]
	s_branch .Lg2_p12_loop

.Lg2_p14_loop:
	ds_read_b128 v[198:201], v214 offset:8192
	ds_read_b128 v[202:205], v214 offset:10240
	ds_read_b128 v[206:209], v214 offset:12288
	ds_read_b128 v[210:213], v214 offset:14336
	s_waitcnt lgkmcnt(4)
	v_mfma_f32_16x16x32_bf16 v[126:129], v[218:221], v[182:185], v[126:129]
	v_mfma_f32_16x16x32_bf16 v[122:125], v[224:227], v[182:185], v[122:125]
	v_mfma_f32_16x16x32_bf16 v[118:121], v[228:231], v[182:185], v[118:121]
	v_mfma_f32_16x16x32_bf16 v[114:117], v[232:235], v[182:185], v[114:117]
	v_mfma_f32_16x16x32_bf16 v[110:113], v[218:221], v[186:189], v[110:113]
	v_mfma_f32_16x16x32_bf16 v[106:109], v[224:227], v[186:189], v[106:109]
	v_mfma_f32_16x16x32_bf16 v[102:105], v[228:231], v[186:189], v[102:105]
	v_mfma_f32_16x16x32_bf16 v[98:101], v[232:235], v[186:189], v[98:101]
	v_mfma_f32_16x16x32_bf16 v[94:97], v[218:221], v[190:193], v[94:97]
	v_mfma_f32_16x16x32_bf16 v[90:93], v[224:227], v[190:193], v[90:93]
	v_mfma_f32_16x16x32_bf16 v[86:89], v[228:231], v[190:193], v[86:89]
	v_mfma_f32_16x16x32_bf16 v[82:85], v[232:235], v[190:193], v[82:85]
	v_mfma_f32_16x16x32_bf16 v[78:81], v[218:221], v[194:197], v[78:81]
	v_mfma_f32_16x16x32_bf16 v[74:77], v[224:227], v[194:197], v[74:77]
	v_mfma_f32_16x16x32_bf16 v[70:73], v[228:231], v[194:197], v[70:73]
	v_mfma_f32_16x16x32_bf16 v[66:69], v[232:235], v[194:197], v[66:69]
	ds_read_b128 v[182:185], v216
	ds_read_b128 v[186:189], v216 offset:2048
	ds_read_b128 v[190:193], v216 offset:4096
	ds_read_b128 v[194:197], v216 offset:6144
	ds_read_b128 v[236:239], v217
	ds_read_b128 v[240:243], v217 offset:2048
	ds_read_b128 v[244:247], v217 offset:4096
	ds_read_b128 v[248:251], v217 offset:6144
	s_waitcnt lgkmcnt(8)
	v_mfma_f32_16x16x32_bf16 v[62:65], v[218:221], v[198:201], v[62:65]
	v_mfma_f32_16x16x32_bf16 v[58:61], v[224:227], v[198:201], v[58:61]
	v_mfma_f32_16x16x32_bf16 v[54:57], v[228:231], v[198:201], v[54:57]
	v_mfma_f32_16x16x32_bf16 v[50:53], v[232:235], v[198:201], v[50:53]
	v_mfma_f32_16x16x32_bf16 v[46:49], v[218:221], v[202:205], v[46:49]
	v_mfma_f32_16x16x32_bf16 v[42:45], v[224:227], v[202:205], v[42:45]
	v_mfma_f32_16x16x32_bf16 v[38:41], v[228:231], v[202:205], v[38:41]
	v_mfma_f32_16x16x32_bf16 v[34:37], v[232:235], v[202:205], v[34:37]
	v_mfma_f32_16x16x32_bf16 v[30:33], v[218:221], v[206:209], v[30:33]
	v_mfma_f32_16x16x32_bf16 v[26:29], v[224:227], v[206:209], v[26:29]
	v_mfma_f32_16x16x32_bf16 v[22:25], v[228:231], v[206:209], v[22:25]
	v_mfma_f32_16x16x32_bf16 v[18:21], v[232:235], v[206:209], v[18:21]
	v_mfma_f32_16x16x32_bf16 v[14:17], v[218:221], v[210:213], v[14:17]
	v_mfma_f32_16x16x32_bf16 v[10:13], v[224:227], v[210:213], v[10:13]
	v_mfma_f32_16x16x32_bf16 v[6:9], v[228:231], v[210:213], v[6:9]
	v_mfma_f32_16x16x32_bf16 v[2:5], v[232:235], v[210:213], v[2:5]
	ds_read_b128 v[198:201], v216 offset:8192
	ds_read_b128 v[202:205], v216 offset:10240
	ds_read_b128 v[206:209], v216 offset:12288
	ds_read_b128 v[210:213], v216 offset:14336
	s_waitcnt lgkmcnt(4)
	s_add_u32 s0, s0, 0x80
	s_addc_u32 s1, s1, 0
	s_add_u32 s98, s98, 0x80
	s_addc_u32 s99, s99, 0
	s_add_u32 s100, s100, 0x80
	s_addc_u32 s101, s101, 0
	s_cmpk_eq_i32 s0, 0x780
	s_cbranch_scc1 .Lg2_p14_last
	v_mfma_f32_16x16x32_bf16 v[126:129], v[236:239], v[182:185], v[126:129]
	s_waitcnt vmcnt(7)
	ds_write_b128 v253, v[150:153]
	v_mfma_f32_16x16x32_bf16 v[122:125], v[240:243], v[182:185], v[122:125]
	v_mfma_f32_16x16x32_bf16 v[118:121], v[244:247], v[182:185], v[118:121]
	s_waitcnt vmcnt(6)
	ds_write_b128 v253, v[154:157] offset:8192
	v_add_u32_e32 v152, s12, v215
	v_mfma_f32_16x16x32_bf16 v[114:117], v[248:251], v[182:185], v[114:117]
	global_load_dwordx4 v[150:153], v152, s[98:99] offset:128
	v_mfma_f32_16x16x32_bf16 v[110:113], v[236:239], v[186:189], v[110:113]
	s_waitcnt vmcnt(6)
	ds_write_b128 v253, v[158:161] offset:16384
	v_add_u32_e32 v154, s13, v215
	v_mfma_f32_16x16x32_bf16 v[106:109], v[240:243], v[186:189], v[106:109]
	global_load_dwordx4 v[154:157], v154, s[98:99] offset:128
	v_mfma_f32_16x16x32_bf16 v[102:105], v[244:247], v[186:189], v[102:105]
	s_waitcnt vmcnt(6)
	ds_write_b128 v253, v[162:165] offset:24576
	v_add_u32_e32 v158, s14, v215
	v_mfma_f32_16x16x32_bf16 v[98:101], v[248:251], v[186:189], v[98:101]
	global_load_dwordx4 v[158:161], v158, s[98:99] offset:128
	v_mfma_f32_16x16x32_bf16 v[94:97], v[236:239], v[190:193], v[94:97]
	s_waitcnt vmcnt(6)
	ds_write_b128 v254, v[166:169]
	v_add_u32_e32 v162, s15, v215
	v_mfma_f32_16x16x32_bf16 v[90:93], v[240:243], v[190:193], v[90:93]
	global_load_dwordx4 v[162:165], v162, s[98:99] offset:128
	v_mfma_f32_16x16x32_bf16 v[86:89], v[244:247], v[190:193], v[86:89]
	s_waitcnt vmcnt(6)
	ds_write_b128 v254, v[170:173] offset:8192
	v_add_u32_e32 v166, s16, v252
	v_mfma_f32_16x16x32_bf16 v[82:85], v[248:251], v[190:193], v[82:85]
	global_load_dwordx4 v[166:169], v166, s[100:101] offset:128
	v_mfma_f32_16x16x32_bf16 v[78:81], v[236:239], v[194:197], v[78:81]
	s_waitcnt vmcnt(6)
	ds_write_b128 v254, v[174:177] offset:16384
	v_add_u32_e32 v170, s17, v252
	v_mfma_f32_16x16x32_bf16 v[74:77], v[240:243], v[194:197], v[74:77]
	global_load_dwordx4 v[170:173], v170, s[100:101] offset:128
	v_mfma_f32_16x16x32_bf16 v[70:73], v[244:247], v[194:197], v[70:73]
	s_waitcnt vmcnt(6)
	ds_write_b128 v254, v[178:181] offset:24576
	v_add_u32_e32 v176, s18, v252
	v_mfma_f32_16x16x32_bf16 v[66:69], v[248:251], v[194:197], v[66:69]
	global_load_dwordx4 v[174:177], v176, s[100:101] offset:128
	v_add_u32_e32 v178, s19, v252
	s_nop 0
	global_load_dwordx4 v[178:181], v178, s[100:101] offset:128
	s_waitcnt lgkmcnt(0)
	s_barrier
	v_xor_b32_e32 v214, 0x8000, v214
	v_xor_b32_e32 v223, 0x8000, v223
	v_xor_b32_e32 v216, 0x8000, v216
	v_xor_b32_e32 v217, 0x8000, v217
	v_xor_b32_e32 v253, 0x8000, v253
	v_xor_b32_e32 v254, 0x8000, v254
	ds_read_b128 v[182:185], v214
	ds_read_b128 v[186:189], v214 offset:2048
	ds_read_b128 v[190:193], v214 offset:4096
	ds_read_b128 v[194:197], v214 offset:6144
	ds_read_b128 v[218:221], v223
	ds_read_b128 v[224:227], v223 offset:2048
	ds_read_b128 v[228:231], v223 offset:4096
	ds_read_b128 v[232:235], v223 offset:6144
	v_mfma_f32_16x16x32_bf16 v[62:65], v[236:239], v[198:201], v[62:65]
	v_mfma_f32_16x16x32_bf16 v[58:61], v[240:243], v[198:201], v[58:61]
	v_mfma_f32_16x16x32_bf16 v[54:57], v[244:247], v[198:201], v[54:57]
	v_mfma_f32_16x16x32_bf16 v[50:53], v[248:251], v[198:201], v[50:53]
	v_mfma_f32_16x16x32_bf16 v[46:49], v[236:239], v[202:205], v[46:49]
	v_mfma_f32_16x16x32_bf16 v[42:45], v[240:243], v[202:205], v[42:45]
	v_mfma_f32_16x16x32_bf16 v[38:41], v[244:247], v[202:205], v[38:41]
	v_mfma_f32_16x16x32_bf16 v[34:37], v[248:251], v[202:205], v[34:37]
	v_mfma_f32_16x16x32_bf16 v[30:33], v[236:239], v[206:209], v[30:33]
	v_mfma_f32_16x16x32_bf16 v[26:29], v[240:243], v[206:209], v[26:29]
	v_mfma_f32_16x16x32_bf16 v[22:25], v[244:247], v[206:209], v[22:25]
	v_mfma_f32_16x16x32_bf16 v[18:21], v[248:251], v[206:209], v[18:21]
	v_mfma_f32_16x16x32_bf16 v[14:17], v[236:239], v[210:213], v[14:17]
	v_mfma_f32_16x16x32_bf16 v[10:13], v[240:243], v[210:213], v[10:13]
	v_mfma_f32_16x16x32_bf16 v[6:9], v[244:247], v[210:213], v[6:9]
	v_mfma_f32_16x16x32_bf16 v[2:5], v[248:251], v[210:213], v[2:5]
	s_branch .Lg2_p14_loop

.Lg2_p15_loop:
	ds_read_b128 v[196:199], v223 offset:8192
	ds_read_b128 v[200:203], v223 offset:10240
	ds_read_b128 v[204:207], v223 offset:12288
	ds_read_b128 v[208:211], v223 offset:14336
	s_waitcnt lgkmcnt(4)
	v_mfma_f32_16x16x32_bf16 v[126:129], v[212:215], v[180:183], v[126:129]
	v_mfma_f32_16x16x32_bf16 v[122:125], v[218:221], v[180:183], v[122:125]
	v_mfma_f32_16x16x32_bf16 v[118:121], v[224:227], v[180:183], v[118:121]
	v_mfma_f32_16x16x32_bf16 v[114:117], v[228:231], v[180:183], v[114:117]
	v_mfma_f32_16x16x32_bf16 v[110:113], v[212:215], v[184:187], v[110:113]
	v_mfma_f32_16x16x32_bf16 v[106:109], v[218:221], v[184:187], v[106:109]
	v_mfma_f32_16x16x32_bf16 v[102:105], v[224:227], v[184:187], v[102:105]
	v_mfma_f32_16x16x32_bf16 v[98:101], v[228:231], v[184:187], v[98:101]
	v_mfma_f32_16x16x32_bf16 v[94:97], v[212:215], v[188:191], v[94:97]
	v_mfma_f32_16x16x32_bf16 v[90:93], v[218:221], v[188:191], v[90:93]
	v_mfma_f32_16x16x32_bf16 v[86:89], v[224:227], v[188:191], v[86:89]
	v_mfma_f32_16x16x32_bf16 v[82:85], v[228:231], v[188:191], v[82:85]
	v_mfma_f32_16x16x32_bf16 v[78:81], v[212:215], v[192:195], v[78:81]
	v_mfma_f32_16x16x32_bf16 v[74:77], v[218:221], v[192:195], v[74:77]
	v_mfma_f32_16x16x32_bf16 v[70:73], v[224:227], v[192:195], v[70:73]
	v_mfma_f32_16x16x32_bf16 v[66:69], v[228:231], v[192:195], v[66:69]
	ds_read_b128 v[180:183], v216
	ds_read_b128 v[184:187], v216 offset:2048
	ds_read_b128 v[188:191], v216 offset:4096
	ds_read_b128 v[192:195], v216 offset:6144
	ds_read_b128 v[232:235], v217
	ds_read_b128 v[236:239], v217 offset:2048
	ds_read_b128 v[240:243], v217 offset:4096
	ds_read_b128 v[244:247], v217 offset:6144
	s_waitcnt lgkmcnt(8)
	v_mfma_f32_16x16x32_bf16 v[62:65], v[212:215], v[196:199], v[62:65]
	v_mfma_f32_16x16x32_bf16 v[58:61], v[218:221], v[196:199], v[58:61]
	v_mfma_f32_16x16x32_bf16 v[54:57], v[224:227], v[196:199], v[54:57]
	v_mfma_f32_16x16x32_bf16 v[50:53], v[228:231], v[196:199], v[50:53]
	v_mfma_f32_16x16x32_bf16 v[46:49], v[212:215], v[200:203], v[46:49]
	v_mfma_f32_16x16x32_bf16 v[42:45], v[218:221], v[200:203], v[42:45]
	v_mfma_f32_16x16x32_bf16 v[38:41], v[224:227], v[200:203], v[38:41]
	v_mfma_f32_16x16x32_bf16 v[34:37], v[228:231], v[200:203], v[34:37]
	v_mfma_f32_16x16x32_bf16 v[30:33], v[212:215], v[204:207], v[30:33]
	v_mfma_f32_16x16x32_bf16 v[26:29], v[218:221], v[204:207], v[26:29]
	v_mfma_f32_16x16x32_bf16 v[22:25], v[224:227], v[204:207], v[22:25]
	v_mfma_f32_16x16x32_bf16 v[18:21], v[228:231], v[204:207], v[18:21]
	v_mfma_f32_16x16x32_bf16 v[14:17], v[212:215], v[208:211], v[14:17]
	v_mfma_f32_16x16x32_bf16 v[10:13], v[218:221], v[208:211], v[10:13]
	v_mfma_f32_16x16x32_bf16 v[6:9], v[224:227], v[208:211], v[6:9]
	v_mfma_f32_16x16x32_bf16 v[2:5], v[228:231], v[208:211], v[2:5]
	ds_read_b128 v[196:199], v216 offset:8192
	ds_read_b128 v[200:203], v216 offset:10240
	ds_read_b128 v[204:207], v216 offset:12288
	ds_read_b128 v[208:211], v216 offset:14336
	s_waitcnt lgkmcnt(4)
	s_add_u32 s8, s8, 0x80
	s_addc_u32 s9, s9, 0
	s_add_u32 s98, s98, 0x80
	s_addc_u32 s99, s99, 0
	s_add_u32 s100, s100, 0x80
	s_addc_u32 s101, s101, 0
	s_cmpk_eq_i32 s8, 0x1580
	s_cbranch_scc1 .Lg2_p15_last
	v_mfma_f32_16x16x32_bf16 v[126:129], v[232:235], v[180:183], v[126:129]
	s_waitcnt vmcnt(7)
	ds_write_b128 v251, v[140:143]
	v_mfma_f32_16x16x32_bf16 v[122:125], v[236:239], v[180:183], v[122:125]
	v_mfma_f32_16x16x32_bf16 v[118:121], v[240:243], v[180:183], v[118:121]
	s_waitcnt vmcnt(6)
	ds_write_b128 v251, v[152:155] offset:8192
	v_add_u32_e32 v142, s16, v248
	v_mfma_f32_16x16x32_bf16 v[114:117], v[244:247], v[180:183], v[114:117]
	global_load_dwordx4 v[140:143], v142, s[98:99] offset:128
	v_mfma_f32_16x16x32_bf16 v[110:113], v[232:235], v[184:187], v[110:113]
	s_waitcnt vmcnt(6)
	ds_write_b128 v251, v[156:159] offset:16384
	v_add_u32_e32 v144, s17, v248
	v_mfma_f32_16x16x32_bf16 v[106:109], v[236:239], v[184:187], v[106:109]
	global_load_dwordx4 v[152:155], v144, s[98:99] offset:128
	v_mfma_f32_16x16x32_bf16 v[102:105], v[240:243], v[184:187], v[102:105]
	s_waitcnt vmcnt(6)
	ds_write_b128 v251, v[160:163] offset:24576
	v_add_u32_e32 v156, s18, v248
	v_mfma_f32_16x16x32_bf16 v[98:101], v[244:247], v[184:187], v[98:101]
	global_load_dwordx4 v[156:159], v156, s[98:99] offset:128
	v_mfma_f32_16x16x32_bf16 v[94:97], v[232:235], v[188:191], v[94:97]
	s_waitcnt vmcnt(6)
	ds_write_b128 v252, v[164:167]
	v_add_u32_e32 v160, s19, v248
	v_mfma_f32_16x16x32_bf16 v[90:93], v[236:239], v[188:191], v[90:93]
	global_load_dwordx4 v[160:163], v160, s[98:99] offset:128
	v_mfma_f32_16x16x32_bf16 v[86:89], v[240:243], v[188:191], v[86:89]
	s_waitcnt vmcnt(6)
	ds_write_b128 v252, v[168:171] offset:8192
	v_add_u32_e32 v164, s20, v250
	v_mfma_f32_16x16x32_bf16 v[82:85], v[244:247], v[188:191], v[82:85]
	global_load_dwordx4 v[164:167], v164, s[100:101] offset:128
	v_mfma_f32_16x16x32_bf16 v[78:81], v[232:235], v[192:195], v[78:81]
	s_waitcnt vmcnt(6)
	ds_write_b128 v252, v[172:175] offset:16384
	v_add_u32_e32 v168, s21, v250
	v_mfma_f32_16x16x32_bf16 v[74:77], v[236:239], v[192:195], v[74:77]
	global_load_dwordx4 v[168:171], v168, s[100:101] offset:128
	v_mfma_f32_16x16x32_bf16 v[70:73], v[240:243], v[192:195], v[70:73]
	s_waitcnt vmcnt(6)
	ds_write_b128 v252, v[176:179] offset:24576
	v_add_u32_e32 v172, s22, v250
	v_mfma_f32_16x16x32_bf16 v[66:69], v[244:247], v[192:195], v[66:69]
	global_load_dwordx4 v[172:175], v172, s[100:101] offset:128
	v_add_u32_e32 v144, s23, v250
	s_nop 0
	global_load_dwordx4 v[176:179], v144, s[100:101] offset:128
	s_waitcnt lgkmcnt(0)
	s_barrier
	v_xor_b32_e32 v223, 0x8000, v223
	v_xor_b32_e32 v249, 0x8000, v249
	v_xor_b32_e32 v216, 0x8000, v216
	v_xor_b32_e32 v217, 0x8000, v217
	v_xor_b32_e32 v251, 0x8000, v251
	v_xor_b32_e32 v252, 0x8000, v252
	ds_read_b128 v[180:183], v223
	ds_read_b128 v[184:187], v223 offset:2048
	ds_read_b128 v[188:191], v223 offset:4096
	ds_read_b128 v[192:195], v223 offset:6144
	ds_read_b128 v[212:215], v249
	ds_read_b128 v[218:221], v249 offset:2048
	ds_read_b128 v[224:227], v249 offset:4096
	ds_read_b128 v[228:231], v249 offset:6144
	v_mfma_f32_16x16x32_bf16 v[62:65], v[232:235], v[196:199], v[62:65]
	v_mfma_f32_16x16x32_bf16 v[58:61], v[236:239], v[196:199], v[58:61]
	v_mfma_f32_16x16x32_bf16 v[54:57], v[240:243], v[196:199], v[54:57]
	v_mfma_f32_16x16x32_bf16 v[50:53], v[244:247], v[196:199], v[50:53]
	v_mfma_f32_16x16x32_bf16 v[46:49], v[232:235], v[200:203], v[46:49]
	v_mfma_f32_16x16x32_bf16 v[42:45], v[236:239], v[200:203], v[42:45]
	v_mfma_f32_16x16x32_bf16 v[38:41], v[240:243], v[200:203], v[38:41]
	v_mfma_f32_16x16x32_bf16 v[34:37], v[244:247], v[200:203], v[34:37]
	v_mfma_f32_16x16x32_bf16 v[30:33], v[232:235], v[204:207], v[30:33]
	v_mfma_f32_16x16x32_bf16 v[26:29], v[236:239], v[204:207], v[26:29]
	v_mfma_f32_16x16x32_bf16 v[22:25], v[240:243], v[204:207], v[22:25]
	v_mfma_f32_16x16x32_bf16 v[18:21], v[244:247], v[204:207], v[18:21]
	v_mfma_f32_16x16x32_bf16 v[14:17], v[232:235], v[208:211], v[14:17]
	v_mfma_f32_16x16x32_bf16 v[10:13], v[236:239], v[208:211], v[10:13]
	v_mfma_f32_16x16x32_bf16 v[6:9], v[240:243], v[208:211], v[6:9]
	v_mfma_f32_16x16x32_bf16 v[2:5], v[244:247], v[208:211], v[2:5]
	s_branch .Lg2_p15_loop
